# v21 plus de-serialised residual epilogues (batched loads, counted waits, deferred atomics) in W_out and FFN2-down GEMM phases
# speedup vs baseline: 1.0038x; 1.0000x over previous
; __device__ __forceinline__ unsigned cvt_pk_bf16(float lo, float hi) { const f32x2 v = {lo, hi}; return __builtin_bit_cast(unsigned, __builtin_convertvector(v, bf16x2_t)); }
;     __device__ __forceinline__ void operator()(const f32x4 (&acc)[2][2][4][2], const Unit& u, int wr, int wc, int fr_, int fq_) const {
;     ...
;         const int row0 = u.pm * 256 + wr * 64 + fr, col0 = u.pn * 256 + wc * 32 + 8 * fq;
; #pragma unroll
;         for (int ai = 0; ai < 2; ++ai)
; #pragma unroll
;             for (int m = 0; m < 4; ++m) {
;                 const int row = row0 + ai * 128 + m * 16; float sq = 0.f;
; #pragma unroll
;                 for (int bj = 0; bj < 2; ++bj) {
;                     const size_t off = (size_t)row * DM + col0 + bj * 128;
;                     f32x4 r0, r1;
;                     if (R) { r0 = *(const f32x4*)(R + off); r1 = *(const f32x4*)(R + off + 4); }
;                     else { const u32x4 rb = *(const u32x4*)(Rb + off); r0 = (f32x4){bflo(rb.x), bfhi(rb.x), bflo(rb.y), bfhi(rb.y)}; r1 = (f32x4){bflo(rb.z), bfhi(rb.z), bflo(rb.w), bfhi(rb.w)}; }
;                     const f32x4 o0 = r0 + acc[ai][bj][m][0] * scale, o1 = r1 + acc[ai][bj][m][1] * scale;
;                     sq += o0[0] * o0[0] + o0[1] * o0[1] + o0[2] * o0[2] + o0[3] * o0[3] + o1[0] * o1[0] + o1[1] * o1[1] + o1[2] * o1[2] + o1[3] * o1[3];
;                     u32x4 w; w.x = cvt_pk_bf16(o0[0], o0[1]); w.y = cvt_pk_bf16(o0[2], o0[3]); w.z = cvt_pk_bf16(o1[0], o1[1]); w.w = cvt_pk_bf16(o1[2], o1[3]);
;                     *(u32x4*)(Xb + off) = w;
;                 }
;                 sq += __shfl_xor(sq, 16); sq += __shfl_xor(sq, 32); if (fq == 0) atomicAdd(ssq + row, sq);
;             }
.LBB0_1344:
	s_lshl_b32 s8, s30, 8
	s_add_i32 s8, s8, s44
	v_add_u32_e32 v142, s8, v145
	s_lshl_b32 s8, s26, 8
	s_or_b32 s8, s8, s45
	v_lshl_add_u32 v140, v144, 3, s8
	v_ashrrev_i32_e32 v143, 31, v142
	v_ashrrev_i32_e32 v141, 31, v140
	v_lshlrev_b64 v[160:161], 11, v[142:143]
	v_lshl_add_u64 v[160:161], v[160:161], 0, v[140:141]
	v_lshl_add_u64 v[162:163], v[160:161], 1, s[54:55]
	v_lshl_add_u64 v[164:165], v[160:161], 1, s[6:7]
	v_lshl_add_u64 v[140:141], v[142:143], 2, s[10:11]
	s_mov_b32 s8, 0x10000
	s_mov_b32 s9, 0
	v_xor_b32_e32 v151, 16, v150
	v_xor_b32_e32 v160, 32, v150
	v_lshlrev_b32_e32 v151, 2, v151
	v_lshlrev_b32_e32 v160, 2, v160
	global_load_dwordx4 v[182:185], v[162:163], off
	global_load_dwordx4 v[186:189], v[162:163], off offset:256
	v_lshl_add_u64 v[162:163], v[162:163], 0, s[8:9]
	global_load_dwordx4 v[190:193], v[162:163], off
	global_load_dwordx4 v[194:197], v[162:163], off offset:256
	v_lshl_add_u64 v[162:163], v[162:163], 0, s[8:9]
	global_load_dwordx4 v[198:201], v[162:163], off
	global_load_dwordx4 v[202:205], v[162:163], off offset:256
	v_lshl_add_u64 v[162:163], v[162:163], 0, s[8:9]
	global_load_dwordx4 v[206:209], v[162:163], off
	global_load_dwordx4 v[210:213], v[162:163], off offset:256
	v_lshl_add_u64 v[162:163], v[162:163], 0, s[8:9]
	v_lshl_add_u64 v[162:163], v[162:163], 0, s[8:9]
	v_lshl_add_u64 v[162:163], v[162:163], 0, s[8:9]
	v_lshl_add_u64 v[162:163], v[162:163], 0, s[8:9]
	v_lshl_add_u64 v[162:163], v[162:163], 0, s[8:9]
	global_load_dwordx4 v[214:217], v[162:163], off
	global_load_dwordx4 v[218:221], v[162:163], off offset:256
	v_lshl_add_u64 v[162:163], v[162:163], 0, s[8:9]
	global_load_dwordx4 v[224:227], v[162:163], off
	global_load_dwordx4 v[228:231], v[162:163], off offset:256
	v_lshl_add_u64 v[162:163], v[162:163], 0, s[8:9]
	global_load_dwordx4 v[232:235], v[162:163], off
	global_load_dwordx4 v[236:239], v[162:163], off offset:256
	v_lshl_add_u64 v[162:163], v[162:163], 0, s[8:9]
	global_load_dwordx4 v[240:243], v[162:163], off
	global_load_dwordx4 v[244:247], v[162:163], off offset:256
	s_waitcnt vmcnt(14)
	v_lshlrev_b32_e32 v174, 16, v182
	v_and_b32_e32 v175, 0xffff0000, v182
	v_lshlrev_b32_e32 v176, 16, v183
	v_and_b32_e32 v177, 0xffff0000, v183
	v_lshlrev_b32_e32 v178, 16, v184
	v_and_b32_e32 v179, 0xffff0000, v184
	v_lshlrev_b32_e32 v180, 16, v185
	v_and_b32_e32 v181, 0xffff0000, v185
	v_add_f32_e32 v174, v124, v174
	v_add_f32_e32 v175, v125, v175
	v_add_f32_e32 v176, v126, v176
	v_add_f32_e32 v177, v127, v177
	v_add_f32_e32 v178, v120, v178
	v_add_f32_e32 v179, v121, v179
	v_add_f32_e32 v180, v122, v180
	v_add_f32_e32 v181, v123, v181
	v_mul_f32_e32 v152, v174, v174
	v_fmac_f32_e32 v152, v175, v175
	v_fmac_f32_e32 v152, v176, v176
	v_fmac_f32_e32 v152, v177, v177
	v_fmac_f32_e32 v152, v178, v178
	v_fmac_f32_e32 v152, v179, v179
	v_fmac_f32_e32 v152, v180, v180
	v_fmac_f32_e32 v152, v181, v181
	v_cvt_pk_bf16_f32 v166, v174, v175
	v_cvt_pk_bf16_f32 v167, v176, v177
	v_cvt_pk_bf16_f32 v168, v178, v179
	v_cvt_pk_bf16_f32 v169, v180, v181
	global_store_dwordx4 v[164:165], v[166:169], off
	v_lshlrev_b32_e32 v174, 16, v186
	v_and_b32_e32 v175, 0xffff0000, v186
	v_lshlrev_b32_e32 v176, 16, v187
	v_and_b32_e32 v177, 0xffff0000, v187
	v_lshlrev_b32_e32 v178, 16, v188
	v_and_b32_e32 v179, 0xffff0000, v188
	v_lshlrev_b32_e32 v180, 16, v189
	v_and_b32_e32 v181, 0xffff0000, v189
	v_add_f32_e32 v174, v116, v174
	v_add_f32_e32 v175, v117, v175
	v_add_f32_e32 v176, v118, v176
	v_add_f32_e32 v177, v119, v177
	v_add_f32_e32 v178, v112, v178
	v_add_f32_e32 v179, v113, v179
	v_add_f32_e32 v180, v114, v180
	v_add_f32_e32 v181, v115, v181
	v_fmac_f32_e32 v152, v174, v174
	v_fmac_f32_e32 v152, v175, v175
	v_fmac_f32_e32 v152, v176, v176
	v_fmac_f32_e32 v152, v177, v177
	v_fmac_f32_e32 v152, v178, v178
	v_fmac_f32_e32 v152, v179, v179
	v_fmac_f32_e32 v152, v180, v180
	v_fmac_f32_e32 v152, v181, v181
	v_cvt_pk_bf16_f32 v170, v174, v175
	v_cvt_pk_bf16_f32 v171, v176, v177
	v_cvt_pk_bf16_f32 v172, v178, v179
	v_cvt_pk_bf16_f32 v173, v180, v181
	global_store_dwordx4 v[164:165], v[170:173], off offset:256
	s_waitcnt vmcnt(14)
	v_lshl_add_u64 v[164:165], v[164:165], 0, s[8:9]
	v_lshlrev_b32_e32 v174, 16, v190
	v_and_b32_e32 v175, 0xffff0000, v190
	v_lshlrev_b32_e32 v176, 16, v191
	v_and_b32_e32 v177, 0xffff0000, v191
	v_lshlrev_b32_e32 v178, 16, v192
	v_and_b32_e32 v179, 0xffff0000, v192
	v_lshlrev_b32_e32 v180, 16, v193
	v_and_b32_e32 v181, 0xffff0000, v193
	v_add_f32_e32 v174, v108, v174
	v_add_f32_e32 v175, v109, v175
	v_add_f32_e32 v176, v110, v176
	v_add_f32_e32 v177, v111, v177
	v_add_f32_e32 v178, v104, v178
	v_add_f32_e32 v179, v105, v179
	v_add_f32_e32 v180, v106, v180
	v_add_f32_e32 v181, v107, v181
	v_mul_f32_e32 v153, v174, v174
	v_fmac_f32_e32 v153, v175, v175
	v_fmac_f32_e32 v153, v176, v176
	v_fmac_f32_e32 v153, v177, v177
	v_fmac_f32_e32 v153, v178, v178
	v_fmac_f32_e32 v153, v179, v179
	v_fmac_f32_e32 v153, v180, v180
	v_fmac_f32_e32 v153, v181, v181
	v_cvt_pk_bf16_f32 v166, v174, v175
	v_cvt_pk_bf16_f32 v167, v176, v177
	v_cvt_pk_bf16_f32 v168, v178, v179
	v_cvt_pk_bf16_f32 v169, v180, v181
	global_store_dwordx4 v[164:165], v[166:169], off
	v_lshlrev_b32_e32 v174, 16, v194
	v_and_b32_e32 v175, 0xffff0000, v194
	v_lshlrev_b32_e32 v176, 16, v195
	v_and_b32_e32 v177, 0xffff0000, v195
	v_lshlrev_b32_e32 v178, 16, v196
	v_and_b32_e32 v179, 0xffff0000, v196
	v_lshlrev_b32_e32 v180, 16, v197
	v_and_b32_e32 v181, 0xffff0000, v197
	v_add_f32_e32 v174, v100, v174
	v_add_f32_e32 v175, v101, v175
	v_add_f32_e32 v176, v102, v176
	v_add_f32_e32 v177, v103, v177
	v_add_f32_e32 v178, v96, v178
	v_add_f32_e32 v179, v97, v179
	v_add_f32_e32 v180, v98, v180
	v_add_f32_e32 v181, v99, v181
	v_fmac_f32_e32 v153, v174, v174
	v_fmac_f32_e32 v153, v175, v175
	v_fmac_f32_e32 v153, v176, v176
	v_fmac_f32_e32 v153, v177, v177
	v_fmac_f32_e32 v153, v178, v178
	v_fmac_f32_e32 v153, v179, v179
	v_fmac_f32_e32 v153, v180, v180
	v_fmac_f32_e32 v153, v181, v181
	v_cvt_pk_bf16_f32 v170, v174, v175
	v_cvt_pk_bf16_f32 v171, v176, v177
	v_cvt_pk_bf16_f32 v172, v178, v179
	v_cvt_pk_bf16_f32 v173, v180, v181
	global_store_dwordx4 v[164:165], v[170:173], off offset:256
	s_waitcnt vmcnt(14)
; __device__ __forceinline__ unsigned cvt_pk_bf16(float lo, float hi) { const f32x2 v = {lo, hi}; return __builtin_bit_cast(unsigned, __builtin_convertvector(v, bf16x2_t)); }
;     __device__ __forceinline__ void operator()(const f32x4 (&acc)[2][2][4][2], const Unit& u, int wr, int wc, int fr_, int fq_) const {
;     ...
;         const int row0 = u.pm * 256 + wr * 64 + fr, col0 = u.pn * 256 + wc * 32 + 8 * fq;
; #pragma unroll
;         for (int ai = 0; ai < 2; ++ai)
; #pragma unroll
;             for (int m = 0; m < 4; ++m) {
;                 const int row = row0 + ai * 128 + m * 16; float sq = 0.f;
; #pragma unroll
;                 for (int bj = 0; bj < 2; ++bj) {
;                     const size_t off = (size_t)row * DM + col0 + bj * 128;
;                     f32x4 r0, r1;
;                     if (R) { r0 = *(const f32x4*)(R + off); r1 = *(const f32x4*)(R + off + 4); }
;                     else { const u32x4 rb = *(const u32x4*)(Rb + off); r0 = (f32x4){bflo(rb.x), bfhi(rb.x), bflo(rb.y), bfhi(rb.y)}; r1 = (f32x4){bflo(rb.z), bfhi(rb.z), bflo(rb.w), bfhi(rb.w)}; }
;                     const f32x4 o0 = r0 + acc[ai][bj][m][0] * scale, o1 = r1 + acc[ai][bj][m][1] * scale;
;                     sq += o0[0] * o0[0] + o0[1] * o0[1] + o0[2] * o0[2] + o0[3] * o0[3] + o1[0] * o1[0] + o1[1] * o1[1] + o1[2] * o1[2] + o1[3] * o1[3];
;                     u32x4 w; w.x = cvt_pk_bf16(o0[0], o0[1]); w.y = cvt_pk_bf16(o0[2], o0[3]); w.z = cvt_pk_bf16(o1[0], o1[1]); w.w = cvt_pk_bf16(o1[2], o1[3]);
;                     *(u32x4*)(Xb + off) = w;
;                 }
;                 sq += __shfl_xor(sq, 16); sq += __shfl_xor(sq, 32); if (fq == 0) atomicAdd(ssq + row, sq);
;             }
	v_lshl_add_u64 v[164:165], v[164:165], 0, s[8:9]
	v_lshlrev_b32_e32 v174, 16, v198
	v_and_b32_e32 v175, 0xffff0000, v198
	v_lshlrev_b32_e32 v176, 16, v199
	v_and_b32_e32 v177, 0xffff0000, v199
	v_lshlrev_b32_e32 v178, 16, v200
	v_and_b32_e32 v179, 0xffff0000, v200
	v_lshlrev_b32_e32 v180, 16, v201
	v_and_b32_e32 v181, 0xffff0000, v201
	v_add_f32_e32 v174, v92, v174
	v_add_f32_e32 v175, v93, v175
	v_add_f32_e32 v176, v94, v176
	v_add_f32_e32 v177, v95, v177
	v_add_f32_e32 v178, v88, v178
	v_add_f32_e32 v179, v89, v179
	v_add_f32_e32 v180, v90, v180
	v_add_f32_e32 v181, v91, v181
	v_mul_f32_e32 v154, v174, v174
	v_fmac_f32_e32 v154, v175, v175
	v_fmac_f32_e32 v154, v176, v176
	v_fmac_f32_e32 v154, v177, v177
	v_fmac_f32_e32 v154, v178, v178
	v_fmac_f32_e32 v154, v179, v179
	v_fmac_f32_e32 v154, v180, v180
	v_fmac_f32_e32 v154, v181, v181
	v_cvt_pk_bf16_f32 v166, v174, v175
	v_cvt_pk_bf16_f32 v167, v176, v177
	v_cvt_pk_bf16_f32 v168, v178, v179
	v_cvt_pk_bf16_f32 v169, v180, v181
	global_store_dwordx4 v[164:165], v[166:169], off
	v_lshlrev_b32_e32 v174, 16, v202
	v_and_b32_e32 v175, 0xffff0000, v202
	v_lshlrev_b32_e32 v176, 16, v203
	v_and_b32_e32 v177, 0xffff0000, v203
	v_lshlrev_b32_e32 v178, 16, v204
	v_and_b32_e32 v179, 0xffff0000, v204
	v_lshlrev_b32_e32 v180, 16, v205
	v_and_b32_e32 v181, 0xffff0000, v205
	v_add_f32_e32 v174, v84, v174
	v_add_f32_e32 v175, v85, v175
	v_add_f32_e32 v176, v86, v176
	v_add_f32_e32 v177, v87, v177
	v_add_f32_e32 v178, v80, v178
	v_add_f32_e32 v179, v81, v179
	v_add_f32_e32 v180, v82, v180
	v_add_f32_e32 v181, v83, v181
	v_fmac_f32_e32 v154, v174, v174
	v_fmac_f32_e32 v154, v175, v175
	v_fmac_f32_e32 v154, v176, v176
	v_fmac_f32_e32 v154, v177, v177
	v_fmac_f32_e32 v154, v178, v178
	v_fmac_f32_e32 v154, v179, v179
	v_fmac_f32_e32 v154, v180, v180
	v_fmac_f32_e32 v154, v181, v181
	v_cvt_pk_bf16_f32 v170, v174, v175
	v_cvt_pk_bf16_f32 v171, v176, v177
	v_cvt_pk_bf16_f32 v172, v178, v179
	v_cvt_pk_bf16_f32 v173, v180, v181
	global_store_dwordx4 v[164:165], v[170:173], off offset:256
	s_waitcnt vmcnt(14)
	v_lshl_add_u64 v[164:165], v[164:165], 0, s[8:9]
	v_lshlrev_b32_e32 v174, 16, v206
	v_and_b32_e32 v175, 0xffff0000, v206
	v_lshlrev_b32_e32 v176, 16, v207
	v_and_b32_e32 v177, 0xffff0000, v207
	v_lshlrev_b32_e32 v178, 16, v208
	v_and_b32_e32 v179, 0xffff0000, v208
	v_lshlrev_b32_e32 v180, 16, v209
	v_and_b32_e32 v181, 0xffff0000, v209
	v_add_f32_e32 v174, v76, v174
	v_add_f32_e32 v175, v77, v175
	v_add_f32_e32 v176, v78, v176
	v_add_f32_e32 v177, v79, v177
	v_add_f32_e32 v178, v72, v178
	v_add_f32_e32 v179, v73, v179
	v_add_f32_e32 v180, v74, v180
	v_add_f32_e32 v181, v75, v181
	v_mul_f32_e32 v155, v174, v174
	v_fmac_f32_e32 v155, v175, v175
	v_fmac_f32_e32 v155, v176, v176
	v_fmac_f32_e32 v155, v177, v177
	v_fmac_f32_e32 v155, v178, v178
	v_fmac_f32_e32 v155, v179, v179
	v_fmac_f32_e32 v155, v180, v180
	v_fmac_f32_e32 v155, v181, v181
	v_cvt_pk_bf16_f32 v166, v174, v175
	v_cvt_pk_bf16_f32 v167, v176, v177
	v_cvt_pk_bf16_f32 v168, v178, v179
	v_cvt_pk_bf16_f32 v169, v180, v181
	global_store_dwordx4 v[164:165], v[166:169], off
	v_lshlrev_b32_e32 v174, 16, v210
	v_and_b32_e32 v175, 0xffff0000, v210
	v_lshlrev_b32_e32 v176, 16, v211
	v_and_b32_e32 v177, 0xffff0000, v211
	v_lshlrev_b32_e32 v178, 16, v212
	v_and_b32_e32 v179, 0xffff0000, v212
	v_lshlrev_b32_e32 v180, 16, v213
	v_and_b32_e32 v181, 0xffff0000, v213
	v_add_f32_e32 v174, v68, v174
	v_add_f32_e32 v175, v69, v175
	v_add_f32_e32 v176, v70, v176
	v_add_f32_e32 v177, v71, v177
	v_add_f32_e32 v178, v64, v178
	v_add_f32_e32 v179, v65, v179
	v_add_f32_e32 v180, v66, v180
	v_add_f32_e32 v181, v67, v181
	v_fmac_f32_e32 v155, v174, v174
	v_fmac_f32_e32 v155, v175, v175
	v_fmac_f32_e32 v155, v176, v176
	v_fmac_f32_e32 v155, v177, v177
	v_fmac_f32_e32 v155, v178, v178
	v_fmac_f32_e32 v155, v179, v179
	v_fmac_f32_e32 v155, v180, v180
	v_fmac_f32_e32 v155, v181, v181
	v_cvt_pk_bf16_f32 v170, v174, v175
	v_cvt_pk_bf16_f32 v171, v176, v177
	v_cvt_pk_bf16_f32 v172, v178, v179
	v_cvt_pk_bf16_f32 v173, v180, v181
	global_store_dwordx4 v[164:165], v[170:173], off offset:256
	s_waitcnt vmcnt(14)
	v_lshl_add_u64 v[164:165], v[164:165], 0, s[8:9]
	v_lshl_add_u64 v[164:165], v[164:165], 0, s[8:9]
	v_lshl_add_u64 v[164:165], v[164:165], 0, s[8:9]
	v_lshl_add_u64 v[164:165], v[164:165], 0, s[8:9]
	v_lshl_add_u64 v[164:165], v[164:165], 0, s[8:9]
	v_lshlrev_b32_e32 v174, 16, v214
	v_and_b32_e32 v175, 0xffff0000, v214
	v_lshlrev_b32_e32 v176, 16, v215
	v_and_b32_e32 v177, 0xffff0000, v215
	v_lshlrev_b32_e32 v178, 16, v216
	v_and_b32_e32 v179, 0xffff0000, v216
	v_lshlrev_b32_e32 v180, 16, v217
	v_and_b32_e32 v181, 0xffff0000, v217
	v_add_f32_e32 v174, v60, v174
	v_add_f32_e32 v175, v61, v175
	v_add_f32_e32 v176, v62, v176
	v_add_f32_e32 v177, v63, v177
	v_add_f32_e32 v178, v56, v178
	v_add_f32_e32 v179, v57, v179
	v_add_f32_e32 v180, v58, v180
	v_add_f32_e32 v181, v59, v181
	v_mul_f32_e32 v156, v174, v174
	v_fmac_f32_e32 v156, v175, v175
	v_fmac_f32_e32 v156, v176, v176
	v_fmac_f32_e32 v156, v177, v177
	v_fmac_f32_e32 v156, v178, v178
	v_fmac_f32_e32 v156, v179, v179
	v_fmac_f32_e32 v156, v180, v180
	v_fmac_f32_e32 v156, v181, v181
	v_cvt_pk_bf16_f32 v166, v174, v175
	v_cvt_pk_bf16_f32 v167, v176, v177
	v_cvt_pk_bf16_f32 v168, v178, v179
	v_cvt_pk_bf16_f32 v169, v180, v181
	global_store_dwordx4 v[164:165], v[166:169], off
	v_lshlrev_b32_e32 v174, 16, v218
	v_and_b32_e32 v175, 0xffff0000, v218
	v_lshlrev_b32_e32 v176, 16, v219
	v_and_b32_e32 v177, 0xffff0000, v219
	v_lshlrev_b32_e32 v178, 16, v220
	v_and_b32_e32 v179, 0xffff0000, v220
	v_lshlrev_b32_e32 v180, 16, v221
	v_and_b32_e32 v181, 0xffff0000, v221
	v_add_f32_e32 v174, v52, v174
	v_add_f32_e32 v175, v53, v175
	v_add_f32_e32 v176, v54, v176
	v_add_f32_e32 v177, v55, v177
	v_add_f32_e32 v178, v48, v178
	v_add_f32_e32 v179, v49, v179
	v_add_f32_e32 v180, v50, v180
	v_add_f32_e32 v181, v51, v181
	v_fmac_f32_e32 v156, v174, v174
	v_fmac_f32_e32 v156, v175, v175
	v_fmac_f32_e32 v156, v176, v176
	v_fmac_f32_e32 v156, v177, v177
	v_fmac_f32_e32 v156, v178, v178
	v_fmac_f32_e32 v156, v179, v179
	v_fmac_f32_e32 v156, v180, v180
	v_fmac_f32_e32 v156, v181, v181
	v_cvt_pk_bf16_f32 v170, v174, v175
	v_cvt_pk_bf16_f32 v171, v176, v177
	v_cvt_pk_bf16_f32 v172, v178, v179
	v_cvt_pk_bf16_f32 v173, v180, v181
	global_store_dwordx4 v[164:165], v[170:173], off offset:256
	s_waitcnt vmcnt(14)
; __device__ __forceinline__ unsigned cvt_pk_bf16(float lo, float hi) { const f32x2 v = {lo, hi}; return __builtin_bit_cast(unsigned, __builtin_convertvector(v, bf16x2_t)); }
;     __device__ __forceinline__ void operator()(const f32x4 (&acc)[2][2][4][2], const Unit& u, int wr, int wc, int fr_, int fq_) const {
;     ...
;         const int row0 = u.pm * 256 + wr * 64 + fr, col0 = u.pn * 256 + wc * 32 + 8 * fq;
; #pragma unroll
;         for (int ai = 0; ai < 2; ++ai)
; #pragma unroll
;             for (int m = 0; m < 4; ++m) {
;                 const int row = row0 + ai * 128 + m * 16; float sq = 0.f;
; #pragma unroll
;                 for (int bj = 0; bj < 2; ++bj) {
;                     const size_t off = (size_t)row * DM + col0 + bj * 128;
;                     f32x4 r0, r1;
;                     if (R) { r0 = *(const f32x4*)(R + off); r1 = *(const f32x4*)(R + off + 4); }
;                     else { const u32x4 rb = *(const u32x4*)(Rb + off); r0 = (f32x4){bflo(rb.x), bfhi(rb.x), bflo(rb.y), bfhi(rb.y)}; r1 = (f32x4){bflo(rb.z), bfhi(rb.z), bflo(rb.w), bfhi(rb.w)}; }
;                     const f32x4 o0 = r0 + acc[ai][bj][m][0] * scale, o1 = r1 + acc[ai][bj][m][1] * scale;
;                     sq += o0[0] * o0[0] + o0[1] * o0[1] + o0[2] * o0[2] + o0[3] * o0[3] + o1[0] * o1[0] + o1[1] * o1[1] + o1[2] * o1[2] + o1[3] * o1[3];
;                     u32x4 w; w.x = cvt_pk_bf16(o0[0], o0[1]); w.y = cvt_pk_bf16(o0[2], o0[3]); w.z = cvt_pk_bf16(o1[0], o1[1]); w.w = cvt_pk_bf16(o1[2], o1[3]);
;                     *(u32x4*)(Xb + off) = w;
;                 }
;                 sq += __shfl_xor(sq, 16); sq += __shfl_xor(sq, 32); if (fq == 0) atomicAdd(ssq + row, sq);
;             }
	v_lshl_add_u64 v[164:165], v[164:165], 0, s[8:9]
	v_lshlrev_b32_e32 v174, 16, v224
	v_and_b32_e32 v175, 0xffff0000, v224
	v_lshlrev_b32_e32 v176, 16, v225
	v_and_b32_e32 v177, 0xffff0000, v225
	v_lshlrev_b32_e32 v178, 16, v226
	v_and_b32_e32 v179, 0xffff0000, v226
	v_lshlrev_b32_e32 v180, 16, v227
	v_and_b32_e32 v181, 0xffff0000, v227
	v_add_f32_e32 v174, v44, v174
	v_add_f32_e32 v175, v45, v175
	v_add_f32_e32 v176, v46, v176
	v_add_f32_e32 v177, v47, v177
	v_add_f32_e32 v178, v40, v178
	v_add_f32_e32 v179, v41, v179
	v_add_f32_e32 v180, v42, v180
	v_add_f32_e32 v181, v43, v181
	v_mul_f32_e32 v157, v174, v174
	v_fmac_f32_e32 v157, v175, v175
	v_fmac_f32_e32 v157, v176, v176
	v_fmac_f32_e32 v157, v177, v177
	v_fmac_f32_e32 v157, v178, v178
	v_fmac_f32_e32 v157, v179, v179
	v_fmac_f32_e32 v157, v180, v180
	v_fmac_f32_e32 v157, v181, v181
	v_cvt_pk_bf16_f32 v166, v174, v175
	v_cvt_pk_bf16_f32 v167, v176, v177
	v_cvt_pk_bf16_f32 v168, v178, v179
	v_cvt_pk_bf16_f32 v169, v180, v181
	global_store_dwordx4 v[164:165], v[166:169], off
	v_lshlrev_b32_e32 v174, 16, v228
	v_and_b32_e32 v175, 0xffff0000, v228
	v_lshlrev_b32_e32 v176, 16, v229
	v_and_b32_e32 v177, 0xffff0000, v229
	v_lshlrev_b32_e32 v178, 16, v230
	v_and_b32_e32 v179, 0xffff0000, v230
	v_lshlrev_b32_e32 v180, 16, v231
	v_and_b32_e32 v181, 0xffff0000, v231
	v_add_f32_e32 v174, v36, v174
	v_add_f32_e32 v175, v37, v175
	v_add_f32_e32 v176, v38, v176
	v_add_f32_e32 v177, v39, v177
	v_add_f32_e32 v178, v32, v178
	v_add_f32_e32 v179, v33, v179
	v_add_f32_e32 v180, v34, v180
	v_add_f32_e32 v181, v35, v181
	v_fmac_f32_e32 v157, v174, v174
	v_fmac_f32_e32 v157, v175, v175
	v_fmac_f32_e32 v157, v176, v176
	v_fmac_f32_e32 v157, v177, v177
	v_fmac_f32_e32 v157, v178, v178
	v_fmac_f32_e32 v157, v179, v179
	v_fmac_f32_e32 v157, v180, v180
	v_fmac_f32_e32 v157, v181, v181
	v_cvt_pk_bf16_f32 v170, v174, v175
	v_cvt_pk_bf16_f32 v171, v176, v177
	v_cvt_pk_bf16_f32 v172, v178, v179
	v_cvt_pk_bf16_f32 v173, v180, v181
	global_store_dwordx4 v[164:165], v[170:173], off offset:256
	s_waitcnt vmcnt(14)
	v_lshl_add_u64 v[164:165], v[164:165], 0, s[8:9]
	v_lshlrev_b32_e32 v174, 16, v232
	v_and_b32_e32 v175, 0xffff0000, v232
	v_lshlrev_b32_e32 v176, 16, v233
	v_and_b32_e32 v177, 0xffff0000, v233
	v_lshlrev_b32_e32 v178, 16, v234
	v_and_b32_e32 v179, 0xffff0000, v234
	v_lshlrev_b32_e32 v180, 16, v235
	v_and_b32_e32 v181, 0xffff0000, v235
	v_add_f32_e32 v174, v28, v174
	v_add_f32_e32 v175, v29, v175
	v_add_f32_e32 v176, v30, v176
	v_add_f32_e32 v177, v31, v177
	v_add_f32_e32 v178, v24, v178
	v_add_f32_e32 v179, v25, v179
	v_add_f32_e32 v180, v26, v180
	v_add_f32_e32 v181, v27, v181
	v_mul_f32_e32 v158, v174, v174
	v_fmac_f32_e32 v158, v175, v175
	v_fmac_f32_e32 v158, v176, v176
	v_fmac_f32_e32 v158, v177, v177
	v_fmac_f32_e32 v158, v178, v178
	v_fmac_f32_e32 v158, v179, v179
	v_fmac_f32_e32 v158, v180, v180
	v_fmac_f32_e32 v158, v181, v181
	v_cvt_pk_bf16_f32 v166, v174, v175
	v_cvt_pk_bf16_f32 v167, v176, v177
	v_cvt_pk_bf16_f32 v168, v178, v179
	v_cvt_pk_bf16_f32 v169, v180, v181
	global_store_dwordx4 v[164:165], v[166:169], off
	v_lshlrev_b32_e32 v174, 16, v236
	v_and_b32_e32 v175, 0xffff0000, v236
	v_lshlrev_b32_e32 v176, 16, v237
	v_and_b32_e32 v177, 0xffff0000, v237
	v_lshlrev_b32_e32 v178, 16, v238
	v_and_b32_e32 v179, 0xffff0000, v238
	v_lshlrev_b32_e32 v180, 16, v239
	v_and_b32_e32 v181, 0xffff0000, v239
	v_add_f32_e32 v174, v20, v174
	v_add_f32_e32 v175, v21, v175
	v_add_f32_e32 v176, v22, v176
	v_add_f32_e32 v177, v23, v177
	v_add_f32_e32 v178, v16, v178
	v_add_f32_e32 v179, v17, v179
	v_add_f32_e32 v180, v18, v180
	v_add_f32_e32 v181, v19, v181
	v_fmac_f32_e32 v158, v174, v174
	v_fmac_f32_e32 v158, v175, v175
	v_fmac_f32_e32 v158, v176, v176
	v_fmac_f32_e32 v158, v177, v177
	v_fmac_f32_e32 v158, v178, v178
	v_fmac_f32_e32 v158, v179, v179
	v_fmac_f32_e32 v158, v180, v180
	v_fmac_f32_e32 v158, v181, v181
	v_cvt_pk_bf16_f32 v170, v174, v175
	v_cvt_pk_bf16_f32 v171, v176, v177
	v_cvt_pk_bf16_f32 v172, v178, v179
	v_cvt_pk_bf16_f32 v173, v180, v181
	global_store_dwordx4 v[164:165], v[170:173], off offset:256
	s_waitcnt vmcnt(14)
; __device__ __forceinline__ unsigned cvt_pk_bf16(float lo, float hi) { const f32x2 v = {lo, hi}; return __builtin_bit_cast(unsigned, __builtin_convertvector(v, bf16x2_t)); }
;     __device__ __forceinline__ void operator()(const f32x4 (&acc)[2][2][4][2], const Unit& u, int wr, int wc, int fr_, int fq_) const {
;     ...
;                 const int row = row0 + ai * 128 + m * 16; float sq = 0.f;
; #pragma unroll
;                 for (int bj = 0; bj < 2; ++bj) {
;                     const size_t off = (size_t)row * DM + col0 + bj * 128;
;                     f32x4 r0, r1;
;                     if (R) { r0 = *(const f32x4*)(R + off); r1 = *(const f32x4*)(R + off + 4); }
;                     else { const u32x4 rb = *(const u32x4*)(Rb + off); r0 = (f32x4){bflo(rb.x), bfhi(rb.x), bflo(rb.y), bfhi(rb.y)}; r1 = (f32x4){bflo(rb.z), bfhi(rb.z), bflo(rb.w), bfhi(rb.w)}; }
;                     const f32x4 o0 = r0 + acc[ai][bj][m][0] * scale, o1 = r1 + acc[ai][bj][m][1] * scale;
;                     sq += o0[0] * o0[0] + o0[1] * o0[1] + o0[2] * o0[2] + o0[3] * o0[3] + o1[0] * o1[0] + o1[1] * o1[1] + o1[2] * o1[2] + o1[3] * o1[3];
;                     u32x4 w; w.x = cvt_pk_bf16(o0[0], o0[1]); w.y = cvt_pk_bf16(o0[2], o0[3]); w.z = cvt_pk_bf16(o1[0], o1[1]); w.w = cvt_pk_bf16(o1[2], o1[3]);
;                     *(u32x4*)(Xb + off) = w;
;                 }
;                 sq += __shfl_xor(sq, 16); sq += __shfl_xor(sq, 32); if (fq == 0) atomicAdd(ssq + row, sq);
	v_lshl_add_u64 v[164:165], v[164:165], 0, s[8:9]
	v_lshlrev_b32_e32 v174, 16, v240
	v_and_b32_e32 v175, 0xffff0000, v240
	v_lshlrev_b32_e32 v176, 16, v241
	v_and_b32_e32 v177, 0xffff0000, v241
	v_lshlrev_b32_e32 v178, 16, v242
	v_and_b32_e32 v179, 0xffff0000, v242
	v_lshlrev_b32_e32 v180, 16, v243
	v_and_b32_e32 v181, 0xffff0000, v243
	v_add_f32_e32 v174, v12, v174
	v_add_f32_e32 v175, v13, v175
	v_add_f32_e32 v176, v14, v176
	v_add_f32_e32 v177, v15, v177
	v_add_f32_e32 v178, v8, v178
	v_add_f32_e32 v179, v9, v179
	v_add_f32_e32 v180, v10, v180
	v_add_f32_e32 v181, v11, v181
	v_mul_f32_e32 v159, v174, v174
	v_fmac_f32_e32 v159, v175, v175
	v_fmac_f32_e32 v159, v176, v176
	v_fmac_f32_e32 v159, v177, v177
	v_fmac_f32_e32 v159, v178, v178
	v_fmac_f32_e32 v159, v179, v179
	v_fmac_f32_e32 v159, v180, v180
	v_fmac_f32_e32 v159, v181, v181
	v_cvt_pk_bf16_f32 v166, v174, v175
	v_cvt_pk_bf16_f32 v167, v176, v177
	v_cvt_pk_bf16_f32 v168, v178, v179
	v_cvt_pk_bf16_f32 v169, v180, v181
	global_store_dwordx4 v[164:165], v[166:169], off
	v_lshlrev_b32_e32 v174, 16, v244
	v_and_b32_e32 v175, 0xffff0000, v244
	v_lshlrev_b32_e32 v176, 16, v245
	v_and_b32_e32 v177, 0xffff0000, v245
	v_lshlrev_b32_e32 v178, 16, v246
	v_and_b32_e32 v179, 0xffff0000, v246
	v_lshlrev_b32_e32 v180, 16, v247
	v_and_b32_e32 v181, 0xffff0000, v247
	v_add_f32_e32 v174, v4, v174
	v_add_f32_e32 v175, v5, v175
	v_add_f32_e32 v176, v6, v176
	v_add_f32_e32 v177, v7, v177
	v_add_f32_e32 v178, v0, v178
	v_add_f32_e32 v179, v1, v179
	v_add_f32_e32 v180, v2, v180
	v_add_f32_e32 v181, v3, v181
	v_fmac_f32_e32 v159, v174, v174
	v_fmac_f32_e32 v159, v175, v175
	v_fmac_f32_e32 v159, v176, v176
	v_fmac_f32_e32 v159, v177, v177
	v_fmac_f32_e32 v159, v178, v178
	v_fmac_f32_e32 v159, v179, v179
	v_fmac_f32_e32 v159, v180, v180
	v_fmac_f32_e32 v159, v181, v181
	v_cvt_pk_bf16_f32 v170, v174, v175
	v_cvt_pk_bf16_f32 v171, v176, v177
	v_cvt_pk_bf16_f32 v172, v178, v179
	v_cvt_pk_bf16_f32 v173, v180, v181
	global_store_dwordx4 v[164:165], v[170:173], off offset:256
	ds_bpermute_b32 v174, v151, v152
	ds_bpermute_b32 v175, v151, v153
	ds_bpermute_b32 v176, v151, v154
	ds_bpermute_b32 v177, v151, v155
	ds_bpermute_b32 v178, v151, v156
	ds_bpermute_b32 v179, v151, v157
	ds_bpermute_b32 v180, v151, v158
	ds_bpermute_b32 v181, v151, v159
	s_waitcnt lgkmcnt(0)
	v_add_f32_e32 v152, v152, v174
	v_add_f32_e32 v153, v153, v175
	v_add_f32_e32 v154, v154, v176
	v_add_f32_e32 v155, v155, v177
	v_add_f32_e32 v156, v156, v178
	v_add_f32_e32 v157, v157, v179
	v_add_f32_e32 v158, v158, v180
	v_add_f32_e32 v159, v159, v181
	ds_bpermute_b32 v174, v160, v152
	ds_bpermute_b32 v175, v160, v153
	ds_bpermute_b32 v176, v160, v154
	ds_bpermute_b32 v177, v160, v155
	ds_bpermute_b32 v178, v160, v156
	ds_bpermute_b32 v179, v160, v157
	ds_bpermute_b32 v180, v160, v158
	ds_bpermute_b32 v181, v160, v159
	s_waitcnt lgkmcnt(0)
	v_add_f32_e32 v152, v152, v174
	v_add_f32_e32 v153, v153, v175
	v_add_f32_e32 v154, v154, v176
	v_add_f32_e32 v155, v155, v177
	v_add_f32_e32 v156, v156, v178
	v_add_f32_e32 v157, v157, v179
	v_add_f32_e32 v158, v158, v180
	v_add_f32_e32 v159, v159, v181
	v_cmp_eq_u32_e32 vcc, 0, v144
	s_and_saveexec_b64 s[8:9], vcc
	s_cbranch_execz .LBB0_1360
	global_atomic_add_f32 v[140:141], v152, off
	global_atomic_add_f32 v[140:141], v153, off offset:64
	global_atomic_add_f32 v[140:141], v154, off offset:128
	global_atomic_add_f32 v[140:141], v155, off offset:192
	global_atomic_add_f32 v[140:141], v156, off offset:512
	global_atomic_add_f32 v[140:141], v157, off offset:576
	global_atomic_add_f32 v[140:141], v158, off offset:640
	global_atomic_add_f32 v[140:141], v159, off offset:704

; __device__ __forceinline__ unsigned cvt_pk_bf16(float lo, float hi) { const f32x2 v = {lo, hi}; return __builtin_bit_cast(unsigned, __builtin_convertvector(v, bf16x2_t)); }
;     __device__ __forceinline__ void operator()(const f32x4 (&acc)[2][2][4][2], const Unit& u, int wr, int wc, int fr_, int fq_) const {
;     ...
;         const int row0 = u.pm * 256 + wr * 64 + fr, col0 = u.pn * 256 + wc * 32 + 8 * fq;
; #pragma unroll
;         for (int ai = 0; ai < 2; ++ai)
; #pragma unroll
;             for (int m = 0; m < 4; ++m) {
;                 const int row = row0 + ai * 128 + m * 16; float sq = 0.f;
; #pragma unroll
;                 for (int bj = 0; bj < 2; ++bj) {
;                     const size_t off = (size_t)row * DM + col0 + bj * 128;
;                     f32x4 r0, r1;
;                     if (R) { r0 = *(const f32x4*)(R + off); r1 = *(const f32x4*)(R + off + 4); }
;                     else { const u32x4 rb = *(const u32x4*)(Rb + off); r0 = (f32x4){bflo(rb.x), bfhi(rb.x), bflo(rb.y), bfhi(rb.y)}; r1 = (f32x4){bflo(rb.z), bfhi(rb.z), bflo(rb.w), bfhi(rb.w)}; }
;                     const f32x4 o0 = r0 + acc[ai][bj][m][0] * scale, o1 = r1 + acc[ai][bj][m][1] * scale;
;                     sq += o0[0] * o0[0] + o0[1] * o0[1] + o0[2] * o0[2] + o0[3] * o0[3] + o1[0] * o1[0] + o1[1] * o1[1] + o1[2] * o1[2] + o1[3] * o1[3];
;                     u32x4 w; w.x = cvt_pk_bf16(o0[0], o0[1]); w.y = cvt_pk_bf16(o0[2], o0[3]); w.z = cvt_pk_bf16(o1[0], o1[1]); w.w = cvt_pk_bf16(o1[2], o1[3]);
;                     *(u32x4*)(Xb + off) = w;
;                 }
;                 sq += __shfl_xor(sq, 16); sq += __shfl_xor(sq, 32); if (fq == 0) atomicAdd(ssq + row, sq);
;             }
.LBB0_1516:
	s_lshl_b32 s8, s60, 8
	s_add_i32 s8, s8, s40
	v_add_u32_e32 v142, s8, v145
	s_lshl_b32 s8, s51, 8
	s_or_b32 s8, s8, s41
	v_lshl_add_u32 v140, v144, 3, s8
	v_ashrrev_i32_e32 v143, 31, v142
	v_ashrrev_i32_e32 v141, 31, v140
	v_lshlrev_b64 v[160:161], 11, v[142:143]
	v_lshl_add_u64 v[160:161], v[160:161], 0, v[140:141]
	v_lshl_add_u64 v[162:163], v[160:161], 1, s[6:7]
	v_lshl_add_u64 v[164:165], v[160:161], 1, s[20:21]
	v_lshl_add_u64 v[140:141], v[142:143], 2, s[10:11]
	s_mov_b32 s8, 0x10000
	s_mov_b32 s9, 0
	v_xor_b32_e32 v151, 16, v150
	v_xor_b32_e32 v160, 32, v150
	v_lshlrev_b32_e32 v151, 2, v151
	v_lshlrev_b32_e32 v160, 2, v160
	global_load_dwordx4 v[182:185], v[162:163], off
	global_load_dwordx4 v[186:189], v[162:163], off offset:256
	v_lshl_add_u64 v[162:163], v[162:163], 0, s[8:9]
	global_load_dwordx4 v[190:193], v[162:163], off
	global_load_dwordx4 v[194:197], v[162:163], off offset:256
	v_lshl_add_u64 v[162:163], v[162:163], 0, s[8:9]
	global_load_dwordx4 v[198:201], v[162:163], off
	global_load_dwordx4 v[202:205], v[162:163], off offset:256
	v_lshl_add_u64 v[162:163], v[162:163], 0, s[8:9]
	global_load_dwordx4 v[206:209], v[162:163], off
	global_load_dwordx4 v[210:213], v[162:163], off offset:256
	v_lshl_add_u64 v[162:163], v[162:163], 0, s[8:9]
	v_lshl_add_u64 v[162:163], v[162:163], 0, s[8:9]
	v_lshl_add_u64 v[162:163], v[162:163], 0, s[8:9]
	v_lshl_add_u64 v[162:163], v[162:163], 0, s[8:9]
	v_lshl_add_u64 v[162:163], v[162:163], 0, s[8:9]
	global_load_dwordx4 v[214:217], v[162:163], off
	global_load_dwordx4 v[218:221], v[162:163], off offset:256
	v_lshl_add_u64 v[162:163], v[162:163], 0, s[8:9]
	global_load_dwordx4 v[224:227], v[162:163], off
	global_load_dwordx4 v[228:231], v[162:163], off offset:256
	v_lshl_add_u64 v[162:163], v[162:163], 0, s[8:9]
	global_load_dwordx4 v[232:235], v[162:163], off
	global_load_dwordx4 v[236:239], v[162:163], off offset:256
	v_lshl_add_u64 v[162:163], v[162:163], 0, s[8:9]
	global_load_dwordx4 v[240:243], v[162:163], off
	global_load_dwordx4 v[244:247], v[162:163], off offset:256
	s_waitcnt vmcnt(14)
	v_lshlrev_b32_e32 v174, 16, v182
	v_and_b32_e32 v175, 0xffff0000, v182
	v_lshlrev_b32_e32 v176, 16, v183
	v_and_b32_e32 v177, 0xffff0000, v183
	v_lshlrev_b32_e32 v178, 16, v184
	v_and_b32_e32 v179, 0xffff0000, v184
	v_lshlrev_b32_e32 v180, 16, v185
	v_and_b32_e32 v181, 0xffff0000, v185
	v_fma_f32 v174, v124, 0.5, v174
	v_fma_f32 v175, v125, 0.5, v175
	v_fma_f32 v176, v126, 0.5, v176
	v_fma_f32 v177, v127, 0.5, v177
	v_fma_f32 v178, v120, 0.5, v178
	v_fma_f32 v179, v121, 0.5, v179
	v_fma_f32 v180, v122, 0.5, v180
	v_fma_f32 v181, v123, 0.5, v181
	v_mul_f32_e32 v152, v174, v174
	v_fmac_f32_e32 v152, v175, v175
	v_fmac_f32_e32 v152, v176, v176
	v_fmac_f32_e32 v152, v177, v177
	v_fmac_f32_e32 v152, v178, v178
	v_fmac_f32_e32 v152, v179, v179
	v_fmac_f32_e32 v152, v180, v180
	v_fmac_f32_e32 v152, v181, v181
	v_cvt_pk_bf16_f32 v166, v174, v175
	v_cvt_pk_bf16_f32 v167, v176, v177
	v_cvt_pk_bf16_f32 v168, v178, v179
	v_cvt_pk_bf16_f32 v169, v180, v181
	global_store_dwordx4 v[164:165], v[166:169], off
	v_lshlrev_b32_e32 v174, 16, v186
	v_and_b32_e32 v175, 0xffff0000, v186
	v_lshlrev_b32_e32 v176, 16, v187
	v_and_b32_e32 v177, 0xffff0000, v187
	v_lshlrev_b32_e32 v178, 16, v188
	v_and_b32_e32 v179, 0xffff0000, v188
	v_lshlrev_b32_e32 v180, 16, v189
	v_and_b32_e32 v181, 0xffff0000, v189
	v_fma_f32 v174, v116, 0.5, v174
	v_fma_f32 v175, v117, 0.5, v175
	v_fma_f32 v176, v118, 0.5, v176
	v_fma_f32 v177, v119, 0.5, v177
	v_fma_f32 v178, v112, 0.5, v178
	v_fma_f32 v179, v113, 0.5, v179
	v_fma_f32 v180, v114, 0.5, v180
	v_fma_f32 v181, v115, 0.5, v181
	v_fmac_f32_e32 v152, v174, v174
	v_fmac_f32_e32 v152, v175, v175
	v_fmac_f32_e32 v152, v176, v176
	v_fmac_f32_e32 v152, v177, v177
	v_fmac_f32_e32 v152, v178, v178
	v_fmac_f32_e32 v152, v179, v179
	v_fmac_f32_e32 v152, v180, v180
	v_fmac_f32_e32 v152, v181, v181
	v_cvt_pk_bf16_f32 v170, v174, v175
	v_cvt_pk_bf16_f32 v171, v176, v177
	v_cvt_pk_bf16_f32 v172, v178, v179
	v_cvt_pk_bf16_f32 v173, v180, v181
	global_store_dwordx4 v[164:165], v[170:173], off offset:256
	s_waitcnt vmcnt(14)
	v_lshl_add_u64 v[164:165], v[164:165], 0, s[8:9]
	v_lshlrev_b32_e32 v174, 16, v190
	v_and_b32_e32 v175, 0xffff0000, v190
	v_lshlrev_b32_e32 v176, 16, v191
	v_and_b32_e32 v177, 0xffff0000, v191
	v_lshlrev_b32_e32 v178, 16, v192
	v_and_b32_e32 v179, 0xffff0000, v192
	v_lshlrev_b32_e32 v180, 16, v193
	v_and_b32_e32 v181, 0xffff0000, v193
	v_fma_f32 v174, v108, 0.5, v174
	v_fma_f32 v175, v109, 0.5, v175
	v_fma_f32 v176, v110, 0.5, v176
	v_fma_f32 v177, v111, 0.5, v177
	v_fma_f32 v178, v104, 0.5, v178
	v_fma_f32 v179, v105, 0.5, v179
	v_fma_f32 v180, v106, 0.5, v180
	v_fma_f32 v181, v107, 0.5, v181
	v_mul_f32_e32 v153, v174, v174
	v_fmac_f32_e32 v153, v175, v175
	v_fmac_f32_e32 v153, v176, v176
	v_fmac_f32_e32 v153, v177, v177
	v_fmac_f32_e32 v153, v178, v178
	v_fmac_f32_e32 v153, v179, v179
	v_fmac_f32_e32 v153, v180, v180
	v_fmac_f32_e32 v153, v181, v181
	v_cvt_pk_bf16_f32 v166, v174, v175
	v_cvt_pk_bf16_f32 v167, v176, v177
	v_cvt_pk_bf16_f32 v168, v178, v179
	v_cvt_pk_bf16_f32 v169, v180, v181
	global_store_dwordx4 v[164:165], v[166:169], off
	v_lshlrev_b32_e32 v174, 16, v194
	v_and_b32_e32 v175, 0xffff0000, v194
	v_lshlrev_b32_e32 v176, 16, v195
	v_and_b32_e32 v177, 0xffff0000, v195
	v_lshlrev_b32_e32 v178, 16, v196
	v_and_b32_e32 v179, 0xffff0000, v196
	v_lshlrev_b32_e32 v180, 16, v197
	v_and_b32_e32 v181, 0xffff0000, v197
	v_fma_f32 v174, v100, 0.5, v174
	v_fma_f32 v175, v101, 0.5, v175
	v_fma_f32 v176, v102, 0.5, v176
	v_fma_f32 v177, v103, 0.5, v177
	v_fma_f32 v178, v96, 0.5, v178
	v_fma_f32 v179, v97, 0.5, v179
	v_fma_f32 v180, v98, 0.5, v180
	v_fma_f32 v181, v99, 0.5, v181
	v_fmac_f32_e32 v153, v174, v174
	v_fmac_f32_e32 v153, v175, v175
	v_fmac_f32_e32 v153, v176, v176
	v_fmac_f32_e32 v153, v177, v177
	v_fmac_f32_e32 v153, v178, v178
	v_fmac_f32_e32 v153, v179, v179
	v_fmac_f32_e32 v153, v180, v180
	v_fmac_f32_e32 v153, v181, v181
	v_cvt_pk_bf16_f32 v170, v174, v175
	v_cvt_pk_bf16_f32 v171, v176, v177
	v_cvt_pk_bf16_f32 v172, v178, v179
	v_cvt_pk_bf16_f32 v173, v180, v181
	global_store_dwordx4 v[164:165], v[170:173], off offset:256
	s_waitcnt vmcnt(14)
; __device__ __forceinline__ unsigned cvt_pk_bf16(float lo, float hi) { const f32x2 v = {lo, hi}; return __builtin_bit_cast(unsigned, __builtin_convertvector(v, bf16x2_t)); }
;     __device__ __forceinline__ void operator()(const f32x4 (&acc)[2][2][4][2], const Unit& u, int wr, int wc, int fr_, int fq_) const {
;     ...
;         const int row0 = u.pm * 256 + wr * 64 + fr, col0 = u.pn * 256 + wc * 32 + 8 * fq;
; #pragma unroll
;         for (int ai = 0; ai < 2; ++ai)
; #pragma unroll
;             for (int m = 0; m < 4; ++m) {
;                 const int row = row0 + ai * 128 + m * 16; float sq = 0.f;
; #pragma unroll
;                 for (int bj = 0; bj < 2; ++bj) {
;                     const size_t off = (size_t)row * DM + col0 + bj * 128;
;                     f32x4 r0, r1;
;                     if (R) { r0 = *(const f32x4*)(R + off); r1 = *(const f32x4*)(R + off + 4); }
;                     else { const u32x4 rb = *(const u32x4*)(Rb + off); r0 = (f32x4){bflo(rb.x), bfhi(rb.x), bflo(rb.y), bfhi(rb.y)}; r1 = (f32x4){bflo(rb.z), bfhi(rb.z), bflo(rb.w), bfhi(rb.w)}; }
;                     const f32x4 o0 = r0 + acc[ai][bj][m][0] * scale, o1 = r1 + acc[ai][bj][m][1] * scale;
;                     sq += o0[0] * o0[0] + o0[1] * o0[1] + o0[2] * o0[2] + o0[3] * o0[3] + o1[0] * o1[0] + o1[1] * o1[1] + o1[2] * o1[2] + o1[3] * o1[3];
;                     u32x4 w; w.x = cvt_pk_bf16(o0[0], o0[1]); w.y = cvt_pk_bf16(o0[2], o0[3]); w.z = cvt_pk_bf16(o1[0], o1[1]); w.w = cvt_pk_bf16(o1[2], o1[3]);
;                     *(u32x4*)(Xb + off) = w;
;                 }
;                 sq += __shfl_xor(sq, 16); sq += __shfl_xor(sq, 32); if (fq == 0) atomicAdd(ssq + row, sq);
;             }
	v_lshl_add_u64 v[164:165], v[164:165], 0, s[8:9]
	v_lshlrev_b32_e32 v174, 16, v198
	v_and_b32_e32 v175, 0xffff0000, v198
	v_lshlrev_b32_e32 v176, 16, v199
	v_and_b32_e32 v177, 0xffff0000, v199
	v_lshlrev_b32_e32 v178, 16, v200
	v_and_b32_e32 v179, 0xffff0000, v200
	v_lshlrev_b32_e32 v180, 16, v201
	v_and_b32_e32 v181, 0xffff0000, v201
	v_fma_f32 v174, v92, 0.5, v174
	v_fma_f32 v175, v93, 0.5, v175
	v_fma_f32 v176, v94, 0.5, v176
	v_fma_f32 v177, v95, 0.5, v177
	v_fma_f32 v178, v88, 0.5, v178
	v_fma_f32 v179, v89, 0.5, v179
	v_fma_f32 v180, v90, 0.5, v180
	v_fma_f32 v181, v91, 0.5, v181
	v_mul_f32_e32 v154, v174, v174
	v_fmac_f32_e32 v154, v175, v175
	v_fmac_f32_e32 v154, v176, v176
	v_fmac_f32_e32 v154, v177, v177
	v_fmac_f32_e32 v154, v178, v178
	v_fmac_f32_e32 v154, v179, v179
	v_fmac_f32_e32 v154, v180, v180
	v_fmac_f32_e32 v154, v181, v181
	v_cvt_pk_bf16_f32 v166, v174, v175
	v_cvt_pk_bf16_f32 v167, v176, v177
	v_cvt_pk_bf16_f32 v168, v178, v179
	v_cvt_pk_bf16_f32 v169, v180, v181
	global_store_dwordx4 v[164:165], v[166:169], off
	v_lshlrev_b32_e32 v174, 16, v202
	v_and_b32_e32 v175, 0xffff0000, v202
	v_lshlrev_b32_e32 v176, 16, v203
	v_and_b32_e32 v177, 0xffff0000, v203
	v_lshlrev_b32_e32 v178, 16, v204
	v_and_b32_e32 v179, 0xffff0000, v204
	v_lshlrev_b32_e32 v180, 16, v205
	v_and_b32_e32 v181, 0xffff0000, v205
	v_fma_f32 v174, v84, 0.5, v174
	v_fma_f32 v175, v85, 0.5, v175
	v_fma_f32 v176, v86, 0.5, v176
	v_fma_f32 v177, v87, 0.5, v177
	v_fma_f32 v178, v80, 0.5, v178
	v_fma_f32 v179, v81, 0.5, v179
	v_fma_f32 v180, v82, 0.5, v180
	v_fma_f32 v181, v83, 0.5, v181
	v_fmac_f32_e32 v154, v174, v174
	v_fmac_f32_e32 v154, v175, v175
	v_fmac_f32_e32 v154, v176, v176
	v_fmac_f32_e32 v154, v177, v177
	v_fmac_f32_e32 v154, v178, v178
	v_fmac_f32_e32 v154, v179, v179
	v_fmac_f32_e32 v154, v180, v180
	v_fmac_f32_e32 v154, v181, v181
	v_cvt_pk_bf16_f32 v170, v174, v175
	v_cvt_pk_bf16_f32 v171, v176, v177
	v_cvt_pk_bf16_f32 v172, v178, v179
	v_cvt_pk_bf16_f32 v173, v180, v181
	global_store_dwordx4 v[164:165], v[170:173], off offset:256
	s_waitcnt vmcnt(14)
	v_lshl_add_u64 v[164:165], v[164:165], 0, s[8:9]
	v_lshlrev_b32_e32 v174, 16, v206
	v_and_b32_e32 v175, 0xffff0000, v206
	v_lshlrev_b32_e32 v176, 16, v207
	v_and_b32_e32 v177, 0xffff0000, v207
	v_lshlrev_b32_e32 v178, 16, v208
	v_and_b32_e32 v179, 0xffff0000, v208
	v_lshlrev_b32_e32 v180, 16, v209
	v_and_b32_e32 v181, 0xffff0000, v209
	v_fma_f32 v174, v76, 0.5, v174
	v_fma_f32 v175, v77, 0.5, v175
	v_fma_f32 v176, v78, 0.5, v176
	v_fma_f32 v177, v79, 0.5, v177
	v_fma_f32 v178, v72, 0.5, v178
	v_fma_f32 v179, v73, 0.5, v179
	v_fma_f32 v180, v74, 0.5, v180
	v_fma_f32 v181, v75, 0.5, v181
	v_mul_f32_e32 v155, v174, v174
	v_fmac_f32_e32 v155, v175, v175
	v_fmac_f32_e32 v155, v176, v176
	v_fmac_f32_e32 v155, v177, v177
	v_fmac_f32_e32 v155, v178, v178
	v_fmac_f32_e32 v155, v179, v179
	v_fmac_f32_e32 v155, v180, v180
	v_fmac_f32_e32 v155, v181, v181
	v_cvt_pk_bf16_f32 v166, v174, v175
	v_cvt_pk_bf16_f32 v167, v176, v177
	v_cvt_pk_bf16_f32 v168, v178, v179
	v_cvt_pk_bf16_f32 v169, v180, v181
	global_store_dwordx4 v[164:165], v[166:169], off
	v_lshlrev_b32_e32 v174, 16, v210
	v_and_b32_e32 v175, 0xffff0000, v210
	v_lshlrev_b32_e32 v176, 16, v211
	v_and_b32_e32 v177, 0xffff0000, v211
	v_lshlrev_b32_e32 v178, 16, v212
	v_and_b32_e32 v179, 0xffff0000, v212
	v_lshlrev_b32_e32 v180, 16, v213
	v_and_b32_e32 v181, 0xffff0000, v213
	v_fma_f32 v174, v68, 0.5, v174
	v_fma_f32 v175, v69, 0.5, v175
	v_fma_f32 v176, v70, 0.5, v176
	v_fma_f32 v177, v71, 0.5, v177
	v_fma_f32 v178, v64, 0.5, v178
	v_fma_f32 v179, v65, 0.5, v179
	v_fma_f32 v180, v66, 0.5, v180
	v_fma_f32 v181, v67, 0.5, v181
	v_fmac_f32_e32 v155, v174, v174
	v_fmac_f32_e32 v155, v175, v175
	v_fmac_f32_e32 v155, v176, v176
	v_fmac_f32_e32 v155, v177, v177
	v_fmac_f32_e32 v155, v178, v178
	v_fmac_f32_e32 v155, v179, v179
	v_fmac_f32_e32 v155, v180, v180
	v_fmac_f32_e32 v155, v181, v181
	v_cvt_pk_bf16_f32 v170, v174, v175
	v_cvt_pk_bf16_f32 v171, v176, v177
	v_cvt_pk_bf16_f32 v172, v178, v179
	v_cvt_pk_bf16_f32 v173, v180, v181
	global_store_dwordx4 v[164:165], v[170:173], off offset:256
	s_waitcnt vmcnt(14)
	v_lshl_add_u64 v[164:165], v[164:165], 0, s[8:9]
	v_lshl_add_u64 v[164:165], v[164:165], 0, s[8:9]
	v_lshl_add_u64 v[164:165], v[164:165], 0, s[8:9]
	v_lshl_add_u64 v[164:165], v[164:165], 0, s[8:9]
	v_lshl_add_u64 v[164:165], v[164:165], 0, s[8:9]
	v_lshlrev_b32_e32 v174, 16, v214
	v_and_b32_e32 v175, 0xffff0000, v214
	v_lshlrev_b32_e32 v176, 16, v215
	v_and_b32_e32 v177, 0xffff0000, v215
	v_lshlrev_b32_e32 v178, 16, v216
	v_and_b32_e32 v179, 0xffff0000, v216
	v_lshlrev_b32_e32 v180, 16, v217
	v_and_b32_e32 v181, 0xffff0000, v217
	v_fma_f32 v174, v60, 0.5, v174
	v_fma_f32 v175, v61, 0.5, v175
	v_fma_f32 v176, v62, 0.5, v176
	v_fma_f32 v177, v63, 0.5, v177
	v_fma_f32 v178, v56, 0.5, v178
	v_fma_f32 v179, v57, 0.5, v179
	v_fma_f32 v180, v58, 0.5, v180
	v_fma_f32 v181, v59, 0.5, v181
	v_mul_f32_e32 v156, v174, v174
	v_fmac_f32_e32 v156, v175, v175
	v_fmac_f32_e32 v156, v176, v176
	v_fmac_f32_e32 v156, v177, v177
	v_fmac_f32_e32 v156, v178, v178
	v_fmac_f32_e32 v156, v179, v179
	v_fmac_f32_e32 v156, v180, v180
	v_fmac_f32_e32 v156, v181, v181
	v_cvt_pk_bf16_f32 v166, v174, v175
	v_cvt_pk_bf16_f32 v167, v176, v177
	v_cvt_pk_bf16_f32 v168, v178, v179
	v_cvt_pk_bf16_f32 v169, v180, v181
	global_store_dwordx4 v[164:165], v[166:169], off
	v_lshlrev_b32_e32 v174, 16, v218
	v_and_b32_e32 v175, 0xffff0000, v218
	v_lshlrev_b32_e32 v176, 16, v219
	v_and_b32_e32 v177, 0xffff0000, v219
	v_lshlrev_b32_e32 v178, 16, v220
	v_and_b32_e32 v179, 0xffff0000, v220
	v_lshlrev_b32_e32 v180, 16, v221
	v_and_b32_e32 v181, 0xffff0000, v221
	v_fma_f32 v174, v52, 0.5, v174
	v_fma_f32 v175, v53, 0.5, v175
	v_fma_f32 v176, v54, 0.5, v176
	v_fma_f32 v177, v55, 0.5, v177
	v_fma_f32 v178, v48, 0.5, v178
	v_fma_f32 v179, v49, 0.5, v179
	v_fma_f32 v180, v50, 0.5, v180
	v_fma_f32 v181, v51, 0.5, v181
	v_fmac_f32_e32 v156, v174, v174
	v_fmac_f32_e32 v156, v175, v175
	v_fmac_f32_e32 v156, v176, v176
	v_fmac_f32_e32 v156, v177, v177
	v_fmac_f32_e32 v156, v178, v178
	v_fmac_f32_e32 v156, v179, v179
	v_fmac_f32_e32 v156, v180, v180
	v_fmac_f32_e32 v156, v181, v181
	v_cvt_pk_bf16_f32 v170, v174, v175
	v_cvt_pk_bf16_f32 v171, v176, v177
	v_cvt_pk_bf16_f32 v172, v178, v179
	v_cvt_pk_bf16_f32 v173, v180, v181
	global_store_dwordx4 v[164:165], v[170:173], off offset:256
	s_waitcnt vmcnt(14)
; __device__ __forceinline__ unsigned cvt_pk_bf16(float lo, float hi) { const f32x2 v = {lo, hi}; return __builtin_bit_cast(unsigned, __builtin_convertvector(v, bf16x2_t)); }
;     __device__ __forceinline__ void operator()(const f32x4 (&acc)[2][2][4][2], const Unit& u, int wr, int wc, int fr_, int fq_) const {
;     ...
;         const int row0 = u.pm * 256 + wr * 64 + fr, col0 = u.pn * 256 + wc * 32 + 8 * fq;
; #pragma unroll
;         for (int ai = 0; ai < 2; ++ai)
; #pragma unroll
;             for (int m = 0; m < 4; ++m) {
;                 const int row = row0 + ai * 128 + m * 16; float sq = 0.f;
; #pragma unroll
;                 for (int bj = 0; bj < 2; ++bj) {
;                     const size_t off = (size_t)row * DM + col0 + bj * 128;
;                     f32x4 r0, r1;
;                     if (R) { r0 = *(const f32x4*)(R + off); r1 = *(const f32x4*)(R + off + 4); }
;                     else { const u32x4 rb = *(const u32x4*)(Rb + off); r0 = (f32x4){bflo(rb.x), bfhi(rb.x), bflo(rb.y), bfhi(rb.y)}; r1 = (f32x4){bflo(rb.z), bfhi(rb.z), bflo(rb.w), bfhi(rb.w)}; }
;                     const f32x4 o0 = r0 + acc[ai][bj][m][0] * scale, o1 = r1 + acc[ai][bj][m][1] * scale;
;                     sq += o0[0] * o0[0] + o0[1] * o0[1] + o0[2] * o0[2] + o0[3] * o0[3] + o1[0] * o1[0] + o1[1] * o1[1] + o1[2] * o1[2] + o1[3] * o1[3];
;                     u32x4 w; w.x = cvt_pk_bf16(o0[0], o0[1]); w.y = cvt_pk_bf16(o0[2], o0[3]); w.z = cvt_pk_bf16(o1[0], o1[1]); w.w = cvt_pk_bf16(o1[2], o1[3]);
;                     *(u32x4*)(Xb + off) = w;
;                 }
;                 sq += __shfl_xor(sq, 16); sq += __shfl_xor(sq, 32); if (fq == 0) atomicAdd(ssq + row, sq);
;             }
	v_lshl_add_u64 v[164:165], v[164:165], 0, s[8:9]
	v_lshlrev_b32_e32 v174, 16, v224
	v_and_b32_e32 v175, 0xffff0000, v224
	v_lshlrev_b32_e32 v176, 16, v225
	v_and_b32_e32 v177, 0xffff0000, v225
	v_lshlrev_b32_e32 v178, 16, v226
	v_and_b32_e32 v179, 0xffff0000, v226
	v_lshlrev_b32_e32 v180, 16, v227
	v_and_b32_e32 v181, 0xffff0000, v227
	v_fma_f32 v174, v44, 0.5, v174
	v_fma_f32 v175, v45, 0.5, v175
	v_fma_f32 v176, v46, 0.5, v176
	v_fma_f32 v177, v47, 0.5, v177
	v_fma_f32 v178, v40, 0.5, v178
	v_fma_f32 v179, v41, 0.5, v179
	v_fma_f32 v180, v42, 0.5, v180
	v_fma_f32 v181, v43, 0.5, v181
	v_mul_f32_e32 v157, v174, v174
	v_fmac_f32_e32 v157, v175, v175
	v_fmac_f32_e32 v157, v176, v176
	v_fmac_f32_e32 v157, v177, v177
	v_fmac_f32_e32 v157, v178, v178
	v_fmac_f32_e32 v157, v179, v179
	v_fmac_f32_e32 v157, v180, v180
	v_fmac_f32_e32 v157, v181, v181
	v_cvt_pk_bf16_f32 v166, v174, v175
	v_cvt_pk_bf16_f32 v167, v176, v177
	v_cvt_pk_bf16_f32 v168, v178, v179
	v_cvt_pk_bf16_f32 v169, v180, v181
	global_store_dwordx4 v[164:165], v[166:169], off
	v_lshlrev_b32_e32 v174, 16, v228
	v_and_b32_e32 v175, 0xffff0000, v228
	v_lshlrev_b32_e32 v176, 16, v229
	v_and_b32_e32 v177, 0xffff0000, v229
	v_lshlrev_b32_e32 v178, 16, v230
	v_and_b32_e32 v179, 0xffff0000, v230
	v_lshlrev_b32_e32 v180, 16, v231
	v_and_b32_e32 v181, 0xffff0000, v231
	v_fma_f32 v174, v36, 0.5, v174
	v_fma_f32 v175, v37, 0.5, v175
	v_fma_f32 v176, v38, 0.5, v176
	v_fma_f32 v177, v39, 0.5, v177
	v_fma_f32 v178, v32, 0.5, v178
	v_fma_f32 v179, v33, 0.5, v179
	v_fma_f32 v180, v34, 0.5, v180
	v_fma_f32 v181, v35, 0.5, v181
	v_fmac_f32_e32 v157, v174, v174
	v_fmac_f32_e32 v157, v175, v175
	v_fmac_f32_e32 v157, v176, v176
	v_fmac_f32_e32 v157, v177, v177
	v_fmac_f32_e32 v157, v178, v178
	v_fmac_f32_e32 v157, v179, v179
	v_fmac_f32_e32 v157, v180, v180
	v_fmac_f32_e32 v157, v181, v181
	v_cvt_pk_bf16_f32 v170, v174, v175
	v_cvt_pk_bf16_f32 v171, v176, v177
	v_cvt_pk_bf16_f32 v172, v178, v179
	v_cvt_pk_bf16_f32 v173, v180, v181
	global_store_dwordx4 v[164:165], v[170:173], off offset:256
	s_waitcnt vmcnt(14)
	v_lshl_add_u64 v[164:165], v[164:165], 0, s[8:9]
	v_lshlrev_b32_e32 v174, 16, v232
	v_and_b32_e32 v175, 0xffff0000, v232
	v_lshlrev_b32_e32 v176, 16, v233
	v_and_b32_e32 v177, 0xffff0000, v233
	v_lshlrev_b32_e32 v178, 16, v234
	v_and_b32_e32 v179, 0xffff0000, v234
	v_lshlrev_b32_e32 v180, 16, v235
	v_and_b32_e32 v181, 0xffff0000, v235
	v_fma_f32 v174, v28, 0.5, v174
	v_fma_f32 v175, v29, 0.5, v175
	v_fma_f32 v176, v30, 0.5, v176
	v_fma_f32 v177, v31, 0.5, v177
	v_fma_f32 v178, v24, 0.5, v178
	v_fma_f32 v179, v25, 0.5, v179
	v_fma_f32 v180, v26, 0.5, v180
	v_fma_f32 v181, v27, 0.5, v181
	v_mul_f32_e32 v158, v174, v174
	v_fmac_f32_e32 v158, v175, v175
	v_fmac_f32_e32 v158, v176, v176
	v_fmac_f32_e32 v158, v177, v177
	v_fmac_f32_e32 v158, v178, v178
	v_fmac_f32_e32 v158, v179, v179
	v_fmac_f32_e32 v158, v180, v180
	v_fmac_f32_e32 v158, v181, v181
	v_cvt_pk_bf16_f32 v166, v174, v175
	v_cvt_pk_bf16_f32 v167, v176, v177
	v_cvt_pk_bf16_f32 v168, v178, v179
	v_cvt_pk_bf16_f32 v169, v180, v181
	global_store_dwordx4 v[164:165], v[166:169], off
	v_lshlrev_b32_e32 v174, 16, v236
	v_and_b32_e32 v175, 0xffff0000, v236
	v_lshlrev_b32_e32 v176, 16, v237
	v_and_b32_e32 v177, 0xffff0000, v237
	v_lshlrev_b32_e32 v178, 16, v238
	v_and_b32_e32 v179, 0xffff0000, v238
	v_lshlrev_b32_e32 v180, 16, v239
	v_and_b32_e32 v181, 0xffff0000, v239
	v_fma_f32 v174, v20, 0.5, v174
	v_fma_f32 v175, v21, 0.5, v175
	v_fma_f32 v176, v22, 0.5, v176
	v_fma_f32 v177, v23, 0.5, v177
	v_fma_f32 v178, v16, 0.5, v178
	v_fma_f32 v179, v17, 0.5, v179
	v_fma_f32 v180, v18, 0.5, v180
	v_fma_f32 v181, v19, 0.5, v181
	v_fmac_f32_e32 v158, v174, v174
	v_fmac_f32_e32 v158, v175, v175
	v_fmac_f32_e32 v158, v176, v176
	v_fmac_f32_e32 v158, v177, v177
	v_fmac_f32_e32 v158, v178, v178
	v_fmac_f32_e32 v158, v179, v179
	v_fmac_f32_e32 v158, v180, v180
	v_fmac_f32_e32 v158, v181, v181
	v_cvt_pk_bf16_f32 v170, v174, v175
	v_cvt_pk_bf16_f32 v171, v176, v177
	v_cvt_pk_bf16_f32 v172, v178, v179
	v_cvt_pk_bf16_f32 v173, v180, v181
	global_store_dwordx4 v[164:165], v[170:173], off offset:256
	s_waitcnt vmcnt(14)
; __device__ __forceinline__ unsigned cvt_pk_bf16(float lo, float hi) { const f32x2 v = {lo, hi}; return __builtin_bit_cast(unsigned, __builtin_convertvector(v, bf16x2_t)); }
;     __device__ __forceinline__ void operator()(const f32x4 (&acc)[2][2][4][2], const Unit& u, int wr, int wc, int fr_, int fq_) const {
;     ...
;                 const int row = row0 + ai * 128 + m * 16; float sq = 0.f;
; #pragma unroll
;                 for (int bj = 0; bj < 2; ++bj) {
;                     const size_t off = (size_t)row * DM + col0 + bj * 128;
;                     f32x4 r0, r1;
;                     if (R) { r0 = *(const f32x4*)(R + off); r1 = *(const f32x4*)(R + off + 4); }
;                     else { const u32x4 rb = *(const u32x4*)(Rb + off); r0 = (f32x4){bflo(rb.x), bfhi(rb.x), bflo(rb.y), bfhi(rb.y)}; r1 = (f32x4){bflo(rb.z), bfhi(rb.z), bflo(rb.w), bfhi(rb.w)}; }
;                     const f32x4 o0 = r0 + acc[ai][bj][m][0] * scale, o1 = r1 + acc[ai][bj][m][1] * scale;
;                     sq += o0[0] * o0[0] + o0[1] * o0[1] + o0[2] * o0[2] + o0[3] * o0[3] + o1[0] * o1[0] + o1[1] * o1[1] + o1[2] * o1[2] + o1[3] * o1[3];
;                     u32x4 w; w.x = cvt_pk_bf16(o0[0], o0[1]); w.y = cvt_pk_bf16(o0[2], o0[3]); w.z = cvt_pk_bf16(o1[0], o1[1]); w.w = cvt_pk_bf16(o1[2], o1[3]);
;                     *(u32x4*)(Xb + off) = w;
;                 }
;                 sq += __shfl_xor(sq, 16); sq += __shfl_xor(sq, 32); if (fq == 0) atomicAdd(ssq + row, sq);
	v_lshl_add_u64 v[164:165], v[164:165], 0, s[8:9]
	v_lshlrev_b32_e32 v174, 16, v240
	v_and_b32_e32 v175, 0xffff0000, v240
	v_lshlrev_b32_e32 v176, 16, v241
	v_and_b32_e32 v177, 0xffff0000, v241
	v_lshlrev_b32_e32 v178, 16, v242
	v_and_b32_e32 v179, 0xffff0000, v242
	v_lshlrev_b32_e32 v180, 16, v243
	v_and_b32_e32 v181, 0xffff0000, v243
	v_fma_f32 v174, v12, 0.5, v174
	v_fma_f32 v175, v13, 0.5, v175
	v_fma_f32 v176, v14, 0.5, v176
	v_fma_f32 v177, v15, 0.5, v177
	v_fma_f32 v178, v8, 0.5, v178
	v_fma_f32 v179, v9, 0.5, v179
	v_fma_f32 v180, v10, 0.5, v180
	v_fma_f32 v181, v11, 0.5, v181
	v_mul_f32_e32 v159, v174, v174
	v_fmac_f32_e32 v159, v175, v175
	v_fmac_f32_e32 v159, v176, v176
	v_fmac_f32_e32 v159, v177, v177
	v_fmac_f32_e32 v159, v178, v178
	v_fmac_f32_e32 v159, v179, v179
	v_fmac_f32_e32 v159, v180, v180
	v_fmac_f32_e32 v159, v181, v181
	v_cvt_pk_bf16_f32 v166, v174, v175
	v_cvt_pk_bf16_f32 v167, v176, v177
	v_cvt_pk_bf16_f32 v168, v178, v179
	v_cvt_pk_bf16_f32 v169, v180, v181
	global_store_dwordx4 v[164:165], v[166:169], off
	v_lshlrev_b32_e32 v174, 16, v244
	v_and_b32_e32 v175, 0xffff0000, v244
	v_lshlrev_b32_e32 v176, 16, v245
	v_and_b32_e32 v177, 0xffff0000, v245
	v_lshlrev_b32_e32 v178, 16, v246
	v_and_b32_e32 v179, 0xffff0000, v246
	v_lshlrev_b32_e32 v180, 16, v247
	v_and_b32_e32 v181, 0xffff0000, v247
	v_fma_f32 v174, v4, 0.5, v174
	v_fma_f32 v175, v5, 0.5, v175
	v_fma_f32 v176, v6, 0.5, v176
	v_fma_f32 v177, v7, 0.5, v177
	v_fma_f32 v178, v0, 0.5, v178
	v_fma_f32 v179, v1, 0.5, v179
	v_fma_f32 v180, v2, 0.5, v180
	v_fma_f32 v181, v3, 0.5, v181
	v_fmac_f32_e32 v159, v174, v174
	v_fmac_f32_e32 v159, v175, v175
	v_fmac_f32_e32 v159, v176, v176
	v_fmac_f32_e32 v159, v177, v177
	v_fmac_f32_e32 v159, v178, v178
	v_fmac_f32_e32 v159, v179, v179
	v_fmac_f32_e32 v159, v180, v180
	v_fmac_f32_e32 v159, v181, v181
	v_cvt_pk_bf16_f32 v170, v174, v175
	v_cvt_pk_bf16_f32 v171, v176, v177
	v_cvt_pk_bf16_f32 v172, v178, v179
	v_cvt_pk_bf16_f32 v173, v180, v181
	global_store_dwordx4 v[164:165], v[170:173], off offset:256
	ds_bpermute_b32 v174, v151, v152
	ds_bpermute_b32 v175, v151, v153
	ds_bpermute_b32 v176, v151, v154
	ds_bpermute_b32 v177, v151, v155
	ds_bpermute_b32 v178, v151, v156
	ds_bpermute_b32 v179, v151, v157
	ds_bpermute_b32 v180, v151, v158
	ds_bpermute_b32 v181, v151, v159
	s_waitcnt lgkmcnt(0)
	v_add_f32_e32 v152, v152, v174
	v_add_f32_e32 v153, v153, v175
	v_add_f32_e32 v154, v154, v176
	v_add_f32_e32 v155, v155, v177
	v_add_f32_e32 v156, v156, v178
	v_add_f32_e32 v157, v157, v179
	v_add_f32_e32 v158, v158, v180
	v_add_f32_e32 v159, v159, v181
	ds_bpermute_b32 v174, v160, v152
	ds_bpermute_b32 v175, v160, v153
	ds_bpermute_b32 v176, v160, v154
	ds_bpermute_b32 v177, v160, v155
	ds_bpermute_b32 v178, v160, v156
	ds_bpermute_b32 v179, v160, v157
	ds_bpermute_b32 v180, v160, v158
	ds_bpermute_b32 v181, v160, v159
	s_waitcnt lgkmcnt(0)
	v_add_f32_e32 v152, v152, v174
	v_add_f32_e32 v153, v153, v175
	v_add_f32_e32 v154, v154, v176
	v_add_f32_e32 v155, v155, v177
	v_add_f32_e32 v156, v156, v178
	v_add_f32_e32 v157, v157, v179
	v_add_f32_e32 v158, v158, v180
	v_add_f32_e32 v159, v159, v181
	v_cmp_eq_u32_e32 vcc, 0, v144
	s_and_saveexec_b64 s[8:9], vcc
	s_cbranch_execz .LBB0_1532
	global_atomic_add_f32 v[140:141], v152, off
	global_atomic_add_f32 v[140:141], v153, off offset:64
	global_atomic_add_f32 v[140:141], v154, off offset:128
	global_atomic_add_f32 v[140:141], v155, off offset:192
	global_atomic_add_f32 v[140:141], v156, off offset:512
	global_atomic_add_f32 v[140:141], v157, off offset:576
	global_atomic_add_f32 v[140:141], v158, off offset:640
	global_atomic_add_f32 v[140:141], v159, off offset:704
